# all seams hand-written (census in the first); seams before FFN1-down and FFN2-down panel-local too, with converter workgroups publishing the converted weights through their own counter
# baseline (speedup 1.0000x reference)
; #define LAS __attribute__((address_space(3)))
; __device__ __forceinline__ unsigned xb_add(unsigned* p, unsigned v) { return __hip_atomic_fetch_add(p, v, __ATOMIC_RELAXED, __HIP_MEMORY_SCOPE_AGENT); }
; __device__ __forceinline__ unsigned xb_xcc_id() { return (unsigned)__builtin_amdgcn_s_getreg((3 << 11) | 20) & 0xFu; }
; __device__ __forceinline__ XcdBarrier xcd_barrier_post(unsigned* bar, volatile LAS unsigned* st) {
;     XcdBarrier b; b.bar = bar; b.x = xb_xcc_id(); b.st = st;
;     if (threadIdx.x == 0) (void)xb_add(&bar[XB_XCNT(b.x)], 1u);
;     return b;
; }
; __global__ void __launch_bounds__(NT, 2) hymba_fwd(Args args) {
;     ...
;     volatile LAS unsigned* MISC = (volatile LAS unsigned*)(lds + MISC_OFF);
;     if (tid < 16) MISC[tid] = 0u;
;     __syncthreads();
;     XcdBarrier xbar = xcd_barrier_post((unsigned*)(ws + WS_BAR), MISC);
.LBB0_4:
	s_or_b64 exec, exec, s[4:5]
	s_waitcnt lgkmcnt(0)
	s_barrier
	s_add_u32 s46, s48, 0x64000
	s_getreg_b32 s4, hwreg(HW_REG_XCC_ID, 0, 4)
	s_addc_u32 s47, s49, 0
	s_and_b32 s33, s4, 15
	v_cmp_eq_u32_e64 s[44:45], 0, v209
	s_and_saveexec_b64 s[4:5], s[44:45]
	s_cbranch_execz .LBB0_7
	s_mov_b64 s[6:7], exec
	v_mbcnt_lo_u32_b32 v0, s6, 0
	v_mbcnt_hi_u32_b32 v0, s7, v0
	v_cmp_eq_u32_e32 vcc, 0, v0
	s_and_b64 s[8:9], exec, vcc
	s_mov_b64 exec, s[8:9]
	s_cbranch_execz .LBB0_7
	s_lshl_b32 s8, s2, 2
	s_add_i32 s8, s8, 0x8000
	s_add_i32 s9, s33, 1
	v_mov_b32_e32 v0, s8
	v_mov_b32_e32 v1, s9
	global_atomic_add v0, v1, s[46:47]
	s_waitcnt vmcnt(0)
	s_lshl_b32 s8, s33, 8
	s_bcnt1_i32_b64 s6, s[6:7]
	v_mov_b32_e32 v0, s8
	v_mov_b32_e32 v1, s6
	global_atomic_add v0, v1, s[46:47] offset:1024

; __device__ __forceinline__ unsigned xb_ld(unsigned* p)              { return __hip_atomic_load(p, __ATOMIC_RELAXED, __HIP_MEMORY_SCOPE_AGENT); }
; __device__ __forceinline__ void xcd_barrier_complete(unsigned* bar, unsigned x, unsigned& nloc, unsigned& nx) {
;     const unsigned G = gridDim.x * gridDim.y * gridDim.z;
;     unsigned sum, cnt, mine, sp = 0u;
;     for (;;) {
;         sum = 0u; cnt = 0u; mine = 0u;
; #pragma unroll
;         for (unsigned j = 0; j < 16; ++j) { const unsigned c = xb_ld(&bar[XB_XCNT(j)]); sum += c; cnt += (c > 0u) ? 1u : 0u; mine = (j == x) ? c : mine; }
;         if (sum == G) break;
;         __builtin_amdgcn_s_sleep(1);
;         if ((++sp & 255u) == 0u) { if (xb_ld(&bar[XB_TMO])) break; if (sp > XB_SPIN_CAP) { atomicAdd(&bar[XB_TMO], 1u); break; } }
;     }
;     nloc = mine > 0u ? mine : 1u; nx = cnt > 0u ? cnt : 1u;
; }
; __device__ __forceinline__ void xcd_barrier(const XcdBarrier& b) {
;     asm volatile("s_waitcnt vmcnt(0)" ::: "memory");
;     __syncthreads();
;     if (threadIdx.x == 0) {
;         unsigned* bar = b.bar;
;         __builtin_amdgcn_s_waitcnt(0);
;         unsigned nloc = b.st[0], nx = b.st[1];
;         if (nloc == 0u) { xcd_barrier_complete(bar, b.x, nloc, nx); b.st[0] = nloc; b.st[1] = nx; }
.LBB0_65:
	s_cmp_gt_i32 s51, 1
	s_cselect_b64 s[4:5], -1, 0
	s_and_b64 s[6:7], s[18:19], s[4:5]
	s_andn2_b64 vcc, exec, s[6:7]
	s_cbranch_vccnz .LBB0_131
	s_cmp_eq_u64 s[44:45], 0
	s_cbranch_scc1 .Lgb0_drain
	s_mov_b64 s[8:9], exec
	s_mov_b64 exec, s[44:45]
	s_lshl_b32 s10, s33, 8
	s_add_u32 s12, s46, s10
	s_addc_u32 s13, s47, 0
	s_mov_b64 exec, s[8:9]
.Lgb0_drain:
	s_waitcnt vmcnt(0) lgkmcnt(0)
	s_barrier
	s_cmp_eq_u64 s[44:45], 0
	s_cbranch_scc1 .Lgb0_end
	s_mov_b64 exec, s[44:45]
	s_mov_b32 s19, 0
	v_mov_b32_e32 v0, 0x400
.Lgb0_census:
	global_load_dword v1, v0, s[46:47] sc1
	global_load_dword v2, v0, s[46:47] offset:256 sc1
	global_load_dword v3, v0, s[46:47] offset:512 sc1
	global_load_dword v4, v0, s[46:47] offset:768 sc1
	global_load_dword v5, v0, s[46:47] offset:1024 sc1
	global_load_dword v6, v0, s[46:47] offset:1280 sc1
	global_load_dword v7, v0, s[46:47] offset:1536 sc1
	global_load_dword v8, v0, s[46:47] offset:1792 sc1
	global_load_dword v9, v0, s[46:47] offset:2048 sc1
	global_load_dword v10, v0, s[46:47] offset:2304 sc1
	global_load_dword v11, v0, s[46:47] offset:2560 sc1
	global_load_dword v12, v0, s[46:47] offset:2816 sc1
	global_load_dword v13, v0, s[46:47] offset:3072 sc1
	global_load_dword v14, v0, s[46:47] offset:3328 sc1
	global_load_dword v15, v0, s[46:47] offset:3584 sc1
	global_load_dword v16, v0, s[46:47] offset:3840 sc1
	global_load_dword v17, v0, s[12:13] sc1
	s_mov_b32 s14, 0
	s_mov_b32 s16, 0
	s_waitcnt vmcnt(0)
	v_readfirstlane_b32 s17, v1
	s_add_i32 s14, s14, s17
	s_cmp_lg_u32 s17, 0
	s_addc_u32 s16, s16, 0
	v_readfirstlane_b32 s17, v2
	s_add_i32 s14, s14, s17
	s_cmp_lg_u32 s17, 0
	s_addc_u32 s16, s16, 0
	v_readfirstlane_b32 s17, v3
	s_add_i32 s14, s14, s17
	s_cmp_lg_u32 s17, 0
	s_addc_u32 s16, s16, 0
	v_readfirstlane_b32 s17, v4
	s_add_i32 s14, s14, s17
	s_cmp_lg_u32 s17, 0
	s_addc_u32 s16, s16, 0
	v_readfirstlane_b32 s17, v5
	s_add_i32 s14, s14, s17
	s_cmp_lg_u32 s17, 0
	s_addc_u32 s16, s16, 0
	v_readfirstlane_b32 s17, v6
	s_add_i32 s14, s14, s17
	s_cmp_lg_u32 s17, 0
	s_addc_u32 s16, s16, 0
	v_readfirstlane_b32 s17, v7
	s_add_i32 s14, s14, s17
	s_cmp_lg_u32 s17, 0
	s_addc_u32 s16, s16, 0
	v_readfirstlane_b32 s17, v8
	s_add_i32 s14, s14, s17
	s_cmp_lg_u32 s17, 0
	s_addc_u32 s16, s16, 0
	v_readfirstlane_b32 s17, v9
	s_add_i32 s14, s14, s17
	s_cmp_lg_u32 s17, 0
	s_addc_u32 s16, s16, 0
	v_readfirstlane_b32 s17, v10
	s_add_i32 s14, s14, s17
	s_cmp_lg_u32 s17, 0
	s_addc_u32 s16, s16, 0
	v_readfirstlane_b32 s17, v11
	s_add_i32 s14, s14, s17
	s_cmp_lg_u32 s17, 0
	s_addc_u32 s16, s16, 0
	v_readfirstlane_b32 s17, v12
	s_add_i32 s14, s14, s17
	s_cmp_lg_u32 s17, 0
	s_addc_u32 s16, s16, 0
	v_readfirstlane_b32 s17, v13
	s_add_i32 s14, s14, s17
	s_cmp_lg_u32 s17, 0
	s_addc_u32 s16, s16, 0
	v_readfirstlane_b32 s17, v14
	s_add_i32 s14, s14, s17
	s_cmp_lg_u32 s17, 0
	s_addc_u32 s16, s16, 0
	v_readfirstlane_b32 s17, v15
	s_add_i32 s14, s14, s17
	s_cmp_lg_u32 s17, 0
	s_addc_u32 s16, s16, 0
	v_readfirstlane_b32 s17, v16
	s_add_i32 s14, s14, s17
	s_cmp_lg_u32 s17, 0
	s_addc_u32 s16, s16, 0
	s_cmp_eq_u32 s14, s3
	s_cbranch_scc1 .Lgb0_census_ok
	s_sleep 1
	s_add_i32 s19, s19, 1
	s_cmp_lt_u32 s19, 20000
	s_cbranch_scc1 .Lgb0_census
.Lgb0_census_ok:
	v_readfirstlane_b32 s15, v17
	s_max_u32 s15, s15, 1
	s_max_u32 s16, s16, 1
	v_mov_b32_e32 v2, s15
	v_mov_b32_e32 v3, s16
	v_mov_b32_e32 v1, 0x23fc0
	ds_write2_b32 v1, v2, v3 offset1:1
	s_xor_b32 s14, s2, 64
	s_lshl_b32 s14, s14, 2
	s_add_i32 s14, s14, 0x8000
	v_mov_b32_e32 v6, s14
	global_load_dword v6, v6, s[46:47] sc1
	s_xor_b32 s14, s2, 128
	s_lshl_b32 s14, s14, 2
	s_add_i32 s14, s14, 0x8000
	v_mov_b32_e32 v7, s14
	global_load_dword v7, v7, s[46:47] sc1
	s_xor_b32 s14, s2, 192
	s_lshl_b32 s14, s14, 2
	s_add_i32 s14, s14, 0x8000
	v_mov_b32_e32 v8, s14
	global_load_dword v8, v8, s[46:47] sc1
	s_add_i32 s14, s33, 1
	s_waitcnt vmcnt(0)
	v_readfirstlane_b32 s17, v6
	v_readfirstlane_b32 s18, v7
	s_cmp_lg_u32 s17, s14
	s_cbranch_scc1 .Lgb0_mis
	v_readfirstlane_b32 s17, v8
	s_cmp_lg_u32 s18, s14
	s_cbranch_scc1 .Lgb0_mis
	s_cmp_eq_u32 s17, s14
	s_cbranch_scc1 .Lgb0_same

; __device__ __forceinline__ unsigned xb_ld(unsigned* p)              { return __hip_atomic_load(p, __ATOMIC_RELAXED, __HIP_MEMORY_SCOPE_AGENT); }
; __device__ __forceinline__ unsigned xb_add(unsigned* p, unsigned v) { return __hip_atomic_fetch_add(p, v, __ATOMIC_RELAXED, __HIP_MEMORY_SCOPE_AGENT); }
; #define XB_SPIN(cond, bar) do { unsigned _sp = 0; while (cond) { __builtin_amdgcn_s_sleep(1); \
;     if ((++_sp & 255u) == 0u) { if (xb_ld(&(bar)[XB_TMO])) break; if (_sp > XB_SPIN_CAP) { atomicAdd(&(bar)[XB_TMO], 1u); break; } } } } while (0)
; __device__ __forceinline__ void xcd_barrier(const XcdBarrier& b) {
;     ...
;         const unsigned old = xb_add(&bar[XB_XSUB(b.x)], 1u);
;         const unsigned gen = old / nloc;
;         if (old + 1u == (gen + 1u) * nloc) {
;             __builtin_amdgcn_fence(__ATOMIC_RELEASE, "agent");
;             asm volatile("s_waitcnt vmcnt(0)" ::: "memory");
;             const unsigned og = xb_add(&bar[XB_TOP], 1u);
;             const unsigned tg = og / nx;
;             if (og + 1u == (tg + 1u) * nx) xb_add(&bar[XB_TOPGEN], 1u);
;             else XB_SPIN(xb_ld(&bar[XB_TOPGEN]) == tg, bar);
;             __builtin_amdgcn_fence(__ATOMIC_ACQUIRE, "agent");
;             xb_add(&bar[XB_XGEN(b.x)], 1u);
;             asm volatile("s_waitcnt vmcnt(0)" ::: "memory");
.Lgb0_same:
	s_mov_b32 s19, 0
	v_mov_b32_e32 v0, 0x10000
	v_mov_b32_e32 v4, 0x1400
	v_mov_b32_e32 v1, 1
	global_atomic_add v4, v4, v1, s[12:13] sc0
	s_add_i32 s17, s100, 1
	s_mul_i32 s18, s17, s15
	s_mul_i32 s17, s17, s16
	s_waitcnt vmcnt(0) lgkmcnt(0)
	v_readfirstlane_b32 s14, v4
	s_add_i32 s14, s14, 1
	s_cmp_lg_u32 s14, s18
	s_cbranch_scc1 .Lgb0_wait
	buffer_wbl2 sc1
	s_waitcnt vmcnt(0)
	global_atomic_add v0, v1, s[46:47]
	global_atomic_add v0, v1, s[46:47] offset:256
	global_atomic_add v0, v1, s[46:47] offset:512
	global_atomic_add v0, v1, s[46:47] offset:768
	global_atomic_add v0, v1, s[46:47] offset:1024
	global_atomic_add v0, v1, s[46:47] offset:1280
	global_atomic_add v0, v1, s[46:47] offset:1536
	global_atomic_add v0, v1, s[46:47] offset:1792
	global_atomic_add v0, v1, s[46:47] offset:2048
	global_atomic_add v0, v1, s[46:47] offset:2304
	global_atomic_add v0, v1, s[46:47] offset:2560
	global_atomic_add v0, v1, s[46:47] offset:2816
	global_atomic_add v0, v1, s[46:47] offset:3072
	global_atomic_add v0, v1, s[46:47] offset:3328
	global_atomic_add v0, v1, s[46:47] offset:3584
	global_atomic_add v0, v1, s[46:47] offset:3840

; #define SEAM(k) do { if (IN(k) && IN((k) + 1)) flat_barrier((unsigned*)(ws + WS_BAR + 65536), fgen, (unsigned)G); } while (0)
; #define SEAM(k) do { if (IN(k) && IN((k) + 1)) xcd_barrier(xbar); } while (0)
; __device__ __forceinline__ void xcd_barrier(const XcdBarrier& b) {
;     ...
;     }
;     __syncthreads();
; }
; __global__ void __launch_bounds__(NT, 2) hymba_fwd(Args args) {
;     ...
;     SEAM(0);
.Lgb0_end:
	s_barrier
	s_add_i32 s100, s100, 1
	s_branch .LBB0_131

; #define SEAM(k) do { if (IN(k) && IN((k) + 1)) flat_barrier((unsigned*)(ws + WS_BAR + 65536), fgen, (unsigned)G); } while (0)
; #define SEAM(k) do { if (IN(k) && IN((k) + 1)) xcd_barrier(xbar); } while (0)
;     __host__ __device__ bool next(int i, Unit& u) const {
;         const long L = (long)i * G + c; if (L >= nwg) return false;
;         int wgid = (int)L; { const int q = nwg / NXCD, r = nwg % NXCD, xcd = wgid % NXCD, off = wgid / NXCD; wgid = (xcd < r ? xcd * (q + 1) : r * (q + 1) + (xcd - r) * q) + off; }
;         const int nig = WGM * nN, gid = wgid / nig, fm = gid * WGM, gsz = (nM - fm) < WGM ? (nM - fm) : WGM;
;         u.pm = fm + ((wgid % nig) % gsz); u.pn = (wgid % nig) / gsz; return true;
; __global__ void __launch_bounds__(NT, 2) hymba_fwd(Args args) {
;     ...
;     if (tid < 16) MISC[tid] = 0u;
;     __syncthreads();
;     XcdBarrier xbar = xcd_barrier_post((unsigned*)(ws + WS_BAR), MISC);
;     if (IN(0)) { for (int rep = 0; rep < NREP(0); ++rep) p0_prologue(args, lds, gw, NGW, wave, lane); }
;     SEAM(0);
;     if (IN(1)) _Pragma("unroll") for (int rep = 0; rep < NREP(1); ++rep) {
;         { pg8::Gemm g{XB, (const bf16*)(ws + WS_WGU1), M, 2 * FF, D}; pg8::StaticOrder S; S.init(M, 2 * FF, G, bx);
;           pg8::EpiSwiglu E{Hb, FF, ssq}; pg8::gemm_phase<pg8::EpiSwiglu, pg8::StaticOrder, true, true>(lds, g, S, E); }
.LBB0_88:
	s_or_b64 exec, exec, s[4:5]
	s_barrier
	v_cmp_gt_u32_e32 vcc, 16, v209
	s_and_saveexec_b64 s[4:5], vcc
	s_cbranch_execnz .LBB0_3
	s_branch .LBB0_4
.LBB0_131:
	s_cmp_lt_i32 s50, 2
	s_cselect_b64 s[6:7], -1, 0
	s_add_u32 s54, s48, 0x3600000
	s_addc_u32 s55, s49, 0
	s_add_u32 s56, s48, 0x6000000
	s_addc_u32 s57, s49, 0
	s_and_b64 s[14:15], s[6:7], s[4:5]
	s_andn2_b64 vcc, exec, s[14:15]
	s_cbranch_vccnz .LBB0_292
	s_cmpk_lt_i32 s2, 0x580
	s_cselect_b64 s[4:5], -1, 0
	s_lshl_b32 s6, s2, 3
	s_add_i32 s12, s88, s6
	s_add_i32 s68, s12, 0xf00
	s_cmpk_lt_i32 s12, 0x1280
	s_waitcnt lgkmcnt(0)
	s_cselect_b64 s[8:9], -1, 0
	s_and_b64 s[6:7], s[8:9], exec
	s_cselect_b32 s69, s68, 0xf00
	s_cmpk_gt_i32 s69, 0xaff
	s_cselect_b64 s[6:7], -1, 0
	s_cmpk_gt_i32 s69, 0xeff
	s_cselect_b64 s[10:11], -1, 0
	v_cndmask_b32_e64 v0, 0, 1, s[10:11]
	s_cmp_lg_u64 s[6:7], 0
	v_readfirstlane_b32 s10, v0
	s_addc_u32 s70, s10, 0
	s_add_i32 s6, s12, 0xfffffb00
	s_add_i32 s25, s12, 0xa00
	s_cmpk_lt_i32 s6, 0x1280
	s_cselect_b64 s[22:23], -1, 0
	s_and_b64 s[6:7], s[22:23], exec
	s_cselect_b32 s59, s25, 0xf00
	s_cmpk_gt_i32 s59, 0xaff
	s_cselect_b64 s[6:7], -1, 0
	s_cmpk_gt_i32 s59, 0xeff
	s_cselect_b64 s[10:11], -1, 0
	v_cndmask_b32_e64 v0, 0, 1, s[10:11]
	s_cmp_lg_u64 s[6:7], 0
	v_readfirstlane_b32 s10, v0
	s_addc_u32 s6, s10, 0
	s_cmpk_gt_i32 s2, 0x57f
	v_readfirstlane_b32 s18, v209
	v_writelane_b32 v248, s6, 2
	s_cbranch_scc1 .LBB0_134
	s_ashr_i32 s6, s2, 31
	s_lshr_b32 s6, s6, 29
	s_add_i32 s6, s2, s6
	s_ashr_i32 s7, s6, 3
	s_and_b32 s6, s6, -8
	s_sub_i32 s6, s2, s6
	s_cmp_lt_i32 s6, 0
	s_movk_i32 s10, 0xb1
	s_cselect_b32 s10, s10, 0xb0
	s_mul_i32 s6, s6, s10
	s_add_i32 s6, s6, s7
	s_mul_hi_i32 s7, s6, 0x2e8ba2e9
	s_lshr_b32 s10, s7, 31
	s_ashr_i32 s7, s7, 5
	s_add_i32 s7, s7, s10
	s_lshl_b32 s10, s7, 3
	s_mulk_i32 s7, 0xb0
	s_sub_i32 s6, s6, s7
	s_sext_i32_i16 s7, s6
	s_bfe_u32 s7, s7, 0x3001c
	s_add_i32 s7, s6, s7
	s_sext_i32_i16 s11, s7
	s_and_b32 s7, s7, 0xfff8
	s_sub_i32 s6, s6, s7
	s_sext_i32_i16 s6, s6
	s_add_i32 s6, s10, s6
	s_ashr_i32 s36, s11, 3

; #define SEAM(k) do { if (IN(k) && IN((k) + 1)) flat_barrier((unsigned*)(ws + WS_BAR + 65536), fgen, (unsigned)G); } while (0)
; #define SEAM(k) do { if (IN(k) && IN((k) + 1)) xcd_barrier(xbar); } while (0)
; __device__ __forceinline__ void panel_sync(unsigned* cnt, int pm, int wid, int lane) {
;     asm volatile("s_waitcnt vmcnt(0) lgkmcnt(0)" ::: "memory"); __builtin_amdgcn_s_barrier(); asm volatile("" ::: "memory");
;     if (wid == 0) {
;         if (lane == 0) { __builtin_amdgcn_fence(__ATOMIC_RELEASE, "agent"); asm volatile("s_waitcnt vmcnt(0)" ::: "memory"); __hip_atomic_fetch_add(cnt + 64 * pm, 1u, __ATOMIC_RELAXED, __HIP_MEMORY_SCOPE_AGENT); }
;         unsigned sp = 0;
;         while ((unsigned)__builtin_amdgcn_readfirstlane(__hip_atomic_load(cnt + 64 * pm, __ATOMIC_RELAXED, __HIP_MEMORY_SCOPE_AGENT)) < 4u) { __builtin_amdgcn_s_sleep(2); if (++sp > (1u << 22)) break; }
; __global__ void __launch_bounds__(NT, 2) hymba_fwd(Args args) {
;     ...
;     SEAM(1);
;     if (IN(2)) {
;         pg8::Gemm g{Hb, (const bf16*)(ws + WS_WD1), M, D, FF}; pg8::StaticOrder S; S.init(M, D, G, bx);
;         pg8::EpiResid E{nullptr  , XB, ssq + M, 0.5f, nullptr}; pg8::gemm_phase<pg8::EpiResid, pg8::StaticOrder, false, true>(lds, g, S, E);
.LBB0_292:
	s_cmp_gt_i32 s51, 2
	s_cselect_b64 s[4:5], -1, 0
	s_and_b64 s[6:7], s[14:15], s[4:5]
	s_andn2_b64 vcc, exec, s[6:7]
	s_cbranch_vccnz .LBB0_346
	v_mov_b32_e32 v1, 0x23fc8
	ds_read_b32 v2, v1
	s_waitcnt lgkmcnt(0)
	v_readfirstlane_b32 s14, v2
	s_cmp_lg_u32 s14, 1
	s_cbranch_scc1 .Lgb1_full
	s_waitcnt vmcnt(0)
	s_barrier
	s_cmp_eq_u64 s[44:45], 0
	s_cbranch_scc1 .Lgb1_gend
	s_mov_b64 s[8:9], exec
	s_mov_b64 exec, s[44:45]
	v_mov_b32_e32 v1, 1
	s_cmp_lt_u32 s2, 160
	s_cbranch_scc1 .Lgb1_gnoconv
	buffer_wbl2 sc1
	s_waitcnt vmcnt(0)
	v_mov_b32_e32 v0, 0x8900
	global_atomic_add v0, v1, s[46:47]
.Lgb1_gnoconv:
	s_and_b32 s10, s2, 63
	s_lshl_b32 s10, s10, 8
	s_add_u32 s12, s46, s10
	s_addc_u32 s13, s47, 0
	v_mov_b32_e32 v0, 0xc000
	global_atomic_add v0, v1, s[12:13]
	s_mov_b32 s19, 0

; #define LAS __attribute__((address_space(3)))
; #define SEAM(k) do { if (IN(k) && IN((k) + 1)) flat_barrier((unsigned*)(ws + WS_BAR + 65536), fgen, (unsigned)G); } while (0)
; #define SEAM(k) do { if (IN(k) && IN((k) + 1)) xcd_barrier(xbar); } while (0)
; __global__ void __launch_bounds__(NT, 2) hymba_fwd(Args args) {
;     ...
;         if (G == 256 && bx >= 160) p0_items(args, (LAS float*)(lds + wave * 16384), P0_EARLY, P0_MID, (bx - 160) * NWAVES + wave, 96 * NWAVES, lane);
;         else if (G != 256) p0_items(args, (LAS float*)(lds + wave * 16384), P0_EARLY, P0_MID, bx * NWAVES + wave, NGW, lane);
;     }
;     SEAM(1);
.Lgb1_gpanel:
	v_mov_b32_e32 v0, 0x8900
.Lgb1_gwpoll:
	global_load_dword v4, v0, s[46:47] sc1
	s_waitcnt vmcnt(0)
	v_readfirstlane_b32 s14, v4
	s_cmp_ge_u32 s14, 96
	s_cbranch_scc1 .Lgb1_gacq
	s_sleep 1
	s_add_i32 s19, s19, 1
	s_cmp_lt_u32 s19, 20000
	s_cbranch_scc1 .Lgb1_gwpoll

; __device__ __forceinline__ unsigned xb_add(unsigned* p, unsigned v) { return __hip_atomic_fetch_add(p, v, __ATOMIC_RELAXED, __HIP_MEMORY_SCOPE_AGENT); }
; __device__ __forceinline__ void xcd_barrier(const XcdBarrier& b) {
;     asm volatile("s_waitcnt vmcnt(0)" ::: "memory");
;     __syncthreads();
;     if (threadIdx.x == 0) {
;         unsigned* bar = b.bar;
;         __builtin_amdgcn_s_waitcnt(0);
;         unsigned nloc = b.st[0], nx = b.st[1];
;         if (nloc == 0u) { xcd_barrier_complete(bar, b.x, nloc, nx); b.st[0] = nloc; b.st[1] = nx; }
;         const unsigned old = xb_add(&bar[XB_XSUB(b.x)], 1u);
;         const unsigned gen = old / nloc;
;         if (old + 1u == (gen + 1u) * nloc) {
.Lgb1_drain:
	s_waitcnt vmcnt(0) lgkmcnt(0)
	s_barrier
	s_cmp_eq_u64 s[44:45], 0
	s_cbranch_scc1 .Lgb1_end
	s_mov_b64 exec, s[44:45]
	s_mov_b32 s19, 0
	v_readfirstlane_b32 s15, v2
	v_readfirstlane_b32 s16, v3
	v_readfirstlane_b32 s14, v5
	s_mul_i32 s17, s100, s16
	s_cmp_ge_u32 s14, s17
	s_cbranch_scc1 .Lgb1_prev_ok

; __device__ __forceinline__ unsigned xb_ld(unsigned* p)              { return __hip_atomic_load(p, __ATOMIC_RELAXED, __HIP_MEMORY_SCOPE_AGENT); }
; __device__ __forceinline__ unsigned xb_add(unsigned* p, unsigned v) { return __hip_atomic_fetch_add(p, v, __ATOMIC_RELAXED, __HIP_MEMORY_SCOPE_AGENT); }
; #define XB_SPIN(cond, bar) do { unsigned _sp = 0; while (cond) { __builtin_amdgcn_s_sleep(1); \
;     if ((++_sp & 255u) == 0u) { if (xb_ld(&(bar)[XB_TMO])) break; if (_sp > XB_SPIN_CAP) { atomicAdd(&(bar)[XB_TMO], 1u); break; } } } } while (0)
; __device__ __forceinline__ void xcd_barrier(const XcdBarrier& b) {
;     ...
;         const unsigned old = xb_add(&bar[XB_XSUB(b.x)], 1u);
;         const unsigned gen = old / nloc;
;         if (old + 1u == (gen + 1u) * nloc) {
;             __builtin_amdgcn_fence(__ATOMIC_RELEASE, "agent");
;             asm volatile("s_waitcnt vmcnt(0)" ::: "memory");
;             const unsigned og = xb_add(&bar[XB_TOP], 1u);
;             const unsigned tg = og / nx;
;             if (og + 1u == (tg + 1u) * nx) xb_add(&bar[XB_TOPGEN], 1u);
;             else XB_SPIN(xb_ld(&bar[XB_TOPGEN]) == tg, bar);
;             __builtin_amdgcn_fence(__ATOMIC_ACQUIRE, "agent");
;             xb_add(&bar[XB_XGEN(b.x)], 1u);
;             asm volatile("s_waitcnt vmcnt(0)" ::: "memory");
.Lgb1_prev_ok:
	v_mov_b32_e32 v4, 0x1400
	v_mov_b32_e32 v1, 1
	global_atomic_add v4, v4, v1, s[12:13] sc0
	s_add_i32 s17, s100, 1
	s_mul_i32 s18, s17, s15
	s_mul_i32 s17, s17, s16
	s_waitcnt vmcnt(0) lgkmcnt(0)
	v_readfirstlane_b32 s14, v4
	s_add_i32 s14, s14, 1
	s_cmp_lg_u32 s14, s18
	s_cbranch_scc1 .Lgb1_wait
	buffer_wbl2 sc1
	s_waitcnt vmcnt(0)
	global_atomic_add v0, v1, s[46:47]
	global_atomic_add v0, v1, s[46:47] offset:256
	global_atomic_add v0, v1, s[46:47] offset:512
	global_atomic_add v0, v1, s[46:47] offset:768
	global_atomic_add v0, v1, s[46:47] offset:1024
	global_atomic_add v0, v1, s[46:47] offset:1280
	global_atomic_add v0, v1, s[46:47] offset:1536
	global_atomic_add v0, v1, s[46:47] offset:1792
	global_atomic_add v0, v1, s[46:47] offset:2048
	global_atomic_add v0, v1, s[46:47] offset:2304
	global_atomic_add v0, v1, s[46:47] offset:2560
	global_atomic_add v0, v1, s[46:47] offset:2816
	global_atomic_add v0, v1, s[46:47] offset:3072
	global_atomic_add v0, v1, s[46:47] offset:3328
	global_atomic_add v0, v1, s[46:47] offset:3584
	global_atomic_add v0, v1, s[46:47] offset:3840

; template <class Epi, class Sched, bool ALIGN_EPI = false, bool SP2 = false>
; __device__ __forceinline__ void gemm_phase(PG8_LAS unsigned char* lds, const Gemm g, const Sched& S, const Epi& E) {
;     const int tid = threadIdx.x, wid = __builtin_amdgcn_readfirstlane(tid >> 6), lane = tid & 63, wr = wid >> 2, wc = wid & 3, fr = lane & 15, fq = lane >> 4;
;     const int K = g.K, nt = K / BK;
;     unsigned voffA[2], voffB[2];
; #pragma unroll
;     for (int i = 0; i < 2; ++i) { int R, C; stage_rc(tid * 16 + i * 8192, R, C); const int Rb = Epi::PERM ? ((R & ~31) + perm32(R & 31)) : R;
;         voffA[i] = (unsigned)(R * K + C) * 2u; voffB[i] = (unsigned)(Rb * K + C) * 2u; }
;     const size_t kstep = (size_t)(BK * 2);
;     const size_t hstep = (size_t)HALF * K * 2;
;     const size_t tstep = 2 * hstep;
;     const unsigned ldsw = (unsigned)wid * 1024u;
; __global__ void __launch_bounds__(NT, 2) hymba_fwd(Args args) {
;     ...
;     if (IN(2)) {
;         pg8::Gemm g{Hb, (const bf16*)(ws + WS_WD1), M, D, FF}; pg8::StaticOrder S; S.init(M, D, G, bx);
;         pg8::EpiResid E{nullptr  , XB, ssq + M, 0.5f, nullptr}; pg8::gemm_phase<pg8::EpiResid, pg8::StaticOrder, false, true>(lds, g, S, E);
.Lgb1_after:
.LBB0_346:
	s_cmp_lt_i32 s50, 3
	s_cselect_b64 s[6:7], -1, 0
	s_waitcnt lgkmcnt(0)
	s_and_b64 s[10:11], s[6:7], s[4:5]
	s_andn2_b64 vcc, exec, s[10:11]
	s_cbranch_vccnz .LBB0_392
	s_cmpk_gt_i32 s2, 0xff
	v_readfirstlane_b32 s25, v209
	s_cbranch_scc1 .LBB0_392
	s_ashr_i32 s26, s2, 31
	s_lshr_b32 s4, s26, 29
	s_add_i32 s7, s2, s4
	s_and_b32 s4, s7, -8
	s_sub_i32 s8, s2, s4
	s_cmp_gt_i32 s8, -1
	s_cbranch_scc0 .LBB0_350
	s_lshl_b32 s6, s8, 5
	s_cbranch_execz .LBB0_351
	s_branch .LBB0_352

; __device__ __forceinline__ void panel_sync(unsigned* cnt, int pm, int wid, int lane) {
;     asm volatile("s_waitcnt vmcnt(0) lgkmcnt(0)" ::: "memory"); __builtin_amdgcn_s_barrier(); asm volatile("" ::: "memory");
;     if (wid == 0) {
;         if (lane == 0) { __builtin_amdgcn_fence(__ATOMIC_RELEASE, "agent"); asm volatile("s_waitcnt vmcnt(0)" ::: "memory"); __hip_atomic_fetch_add(cnt + 64 * pm, 1u, __ATOMIC_RELAXED, __HIP_MEMORY_SCOPE_AGENT); }
;         unsigned sp = 0;
;         while ((unsigned)__builtin_amdgcn_readfirstlane(__hip_atomic_load(cnt + 64 * pm, __ATOMIC_RELAXED, __HIP_MEMORY_SCOPE_AGENT)) < 4u) { __builtin_amdgcn_s_sleep(2); if (++sp > (1u << 22)) break; }
.LBB0_1035:
	s_cmp_gt_i32 s51, 8
	s_cselect_b64 s[4:5], -1, 0
	s_and_b64 s[6:7], s[8:9], s[4:5]
	s_andn2_b64 vcc, exec, s[6:7]
	s_cbranch_vccnz .LBB0_1089
	v_mov_b32_e32 v1, 0x23fc8
	ds_read_b32 v2, v1
	s_waitcnt lgkmcnt(0)
	v_readfirstlane_b32 s14, v2
	s_cmp_lg_u32 s14, 1
	s_cbranch_scc1 .Lgb6_full
	s_waitcnt vmcnt(0)
	s_barrier
	s_cmp_eq_u64 s[44:45], 0
	s_cbranch_scc1 .Lgb6_gend
	s_mov_b64 s[8:9], exec
	s_mov_b64 exec, s[44:45]
	v_mov_b32_e32 v1, 1
	s_and_b32 s10, s2, 63
	s_lshl_b32 s10, s10, 8
	s_add_u32 s12, s46, s10
	s_addc_u32 s13, s47, 0
	v_mov_b32_e32 v0, 0xc000
	global_atomic_add v0, v1, s[12:13]
	s_mov_b32 s19, 0

; __device__ __forceinline__ void panel_sync(unsigned* cnt, int pm, int wid, int lane) {
;     ...
;         __builtin_amdgcn_fence(__ATOMIC_ACQUIRE, "agent");
;         asm volatile("s_waitcnt vmcnt(0)" ::: "memory");
;     }
;     asm volatile("" ::: "memory"); __builtin_amdgcn_s_barrier(); asm volatile("" ::: "memory");
.Lgb6_gpanel:
.Lgb6_gacq:
	buffer_inv sc1
	s_waitcnt vmcnt(0)
	s_mov_b64 exec, s[8:9]

; __device__ __forceinline__ void panel_sync(unsigned* cnt, int pm, int wid, int lane) {
;     asm volatile("s_waitcnt vmcnt(0) lgkmcnt(0)" ::: "memory"); __builtin_amdgcn_s_barrier(); asm volatile("" ::: "memory");
;     if (wid == 0) {
;         if (lane == 0) { __builtin_amdgcn_fence(__ATOMIC_RELEASE, "agent"); asm volatile("s_waitcnt vmcnt(0)" ::: "memory"); __hip_atomic_fetch_add(cnt + 64 * pm, 1u, __ATOMIC_RELAXED, __HIP_MEMORY_SCOPE_AGENT); }
;         unsigned sp = 0;
;         while ((unsigned)__builtin_amdgcn_readfirstlane(__hip_atomic_load(cnt + 64 * pm, __ATOMIC_RELAXED, __HIP_MEMORY_SCOPE_AGENT)) < 4u) { __builtin_amdgcn_s_sleep(2); if (++sp > (1u << 22)) break; }
.LBB0_1111:
	s_cmp_gt_u32 s51, 9
	s_cselect_b64 s[4:5], -1, 0
	s_and_b64 s[4:5], s[8:9], s[4:5]
	s_andn2_b64 vcc, exec, s[4:5]
	s_cbranch_vccnz .LBB0_1165
	v_mov_b32_e32 v1, 0x23fc8
	ds_read_b32 v2, v1
	s_waitcnt lgkmcnt(0)
	v_readfirstlane_b32 s14, v2
	s_cmp_lg_u32 s14, 1
	s_cbranch_scc1 .Lgb7_full
	s_waitcnt vmcnt(0)
	s_barrier
	s_cmp_eq_u64 s[44:45], 0
	s_cbranch_scc1 .Lgb7_gend
	s_mov_b64 s[8:9], exec
	s_mov_b64 exec, s[44:45]
	v_mov_b32_e32 v1, 1
	s_and_b32 s10, s2, 63
	s_lshl_b32 s10, s10, 8
	s_add_u32 s12, s46, s10
	s_addc_u32 s13, s47, 0
	v_mov_b32_e32 v0, 0xc000
	global_atomic_add v0, v1, s[12:13]
	s_mov_b32 s19, 0

; __device__ __forceinline__ void panel_sync(unsigned* cnt, int pm, int wid, int lane) {
;     asm volatile("s_waitcnt vmcnt(0) lgkmcnt(0)" ::: "memory"); __builtin_amdgcn_s_barrier(); asm volatile("" ::: "memory");
;     if (wid == 0) {
;         if (lane == 0) { __builtin_amdgcn_fence(__ATOMIC_RELEASE, "agent"); asm volatile("s_waitcnt vmcnt(0)" ::: "memory"); __hip_atomic_fetch_add(cnt + 64 * pm, 1u, __ATOMIC_RELAXED, __HIP_MEMORY_SCOPE_AGENT); }
;         unsigned sp = 0;
;         while ((unsigned)__builtin_amdgcn_readfirstlane(__hip_atomic_load(cnt + 64 * pm, __ATOMIC_RELAXED, __HIP_MEMORY_SCOPE_AGENT)) < 4u) { __builtin_amdgcn_s_sleep(2); if (++sp > (1u << 22)) break; }
;         __builtin_amdgcn_fence(__ATOMIC_ACQUIRE, "agent");
;         asm volatile("s_waitcnt vmcnt(0)" ::: "memory");
.LBB0_1207:
	s_cmp_gt_i32 s51, 11
	s_cselect_b64 s[4:5], -1, 0
	s_and_b64 s[6:7], s[8:9], s[4:5]
	s_andn2_b64 vcc, exec, s[6:7]
	s_cbranch_vccnz .LBB0_1261
	v_mov_b32_e32 v1, 0x23fc8
	ds_read_b32 v2, v1
	s_waitcnt lgkmcnt(0)
	v_readfirstlane_b32 s14, v2
	s_cmp_lg_u32 s14, 1
	s_cbranch_scc1 .Lgb8_full
	s_waitcnt vmcnt(0)
	s_barrier
	s_cmp_eq_u64 s[44:45], 0
	s_cbranch_scc1 .Lgb8_gend
	s_mov_b64 s[8:9], exec
	s_mov_b64 exec, s[44:45]
	v_mov_b32_e32 v1, 1
	s_and_b32 s10, s2, 63
	s_lshl_b32 s10, s10, 8
	s_add_u32 s12, s46, s10
	s_addc_u32 s13, s47, 0
	v_mov_b32_e32 v0, 0xc000
	global_atomic_add v0, v1, s[12:13]
	s_mov_b32 s19, 0
.Lgb8_gpoll:
	global_load_dword v4, v0, s[12:13] sc1
	s_waitcnt vmcnt(0)
	v_readfirstlane_b32 s14, v4
	s_cmp_ge_u32 s14, 16
	s_cbranch_scc1 .Lgb8_gpanel
	s_sleep 1
	s_add_i32 s19, s19, 1
	s_cmp_lt_u32 s19, 20000
	s_cbranch_scc1 .Lgb8_gpoll

; #define LAS __attribute__((address_space(3)))
; #define SEAM(k) do { if (IN(k) && IN((k) + 1)) flat_barrier((unsigned*)(ws + WS_BAR + 65536), fgen, (unsigned)G); } while (0)
; #define SEAM(k) do { if (IN(k) && IN((k) + 1)) xcd_barrier(xbar); } while (0)
; __global__ void __launch_bounds__(NT, 2) hymba_fwd(Args args) {
;     ...
;         if (G == 256 && bx >= 128) p0_items(args, (LAS float*)(lds + wave * 16384), P0_GU2, P0_ALL, (bx - 128) * NWAVES + wave, 128 * NWAVES, lane);
;         else if (G != 256) p0_items(args, (LAS float*)(lds + wave * 16384), P0_GU2, P0_ALL, bx * NWAVES + wave, NGW, lane);
;     }
;     SEAM(11);
;     if (IN(12)) {
;         pg8::Gemm g{Hb, (const bf16*)(ws + WS_WD2), M, D, FF}; pg8::StaticOrder S; S.init(M, D, G, bx);
;         pg8::EpiFinal E{XB, args.out, ssq + 4 * M, (unsigned*)(ws + WS_CNT), args.in[I_FINN], 0.5f}; pg8::gemm_phase<pg8::EpiFinal, pg8::StaticOrder, false, true>(lds, g, S, E);
.LBB0_1356:
	s_cmp_gt_i32 s51, 12
	s_cselect_b64 s[4:5], -1, 0
	s_and_b64 s[6:7], s[14:15], s[4:5]
	s_andn2_b64 vcc, exec, s[6:7]
	s_cbranch_vccnz .LBB0_1410
	v_mov_b32_e32 v1, 0x23fc8
	ds_read_b32 v2, v1
	s_waitcnt lgkmcnt(0)
	v_readfirstlane_b32 s14, v2
	s_cmp_lg_u32 s14, 1
	s_cbranch_scc1 .Lgb9_full
	s_waitcnt vmcnt(0)
	s_barrier
	s_cmp_eq_u64 s[44:45], 0
	s_cbranch_scc1 .Lgb9_gend
	s_mov_b64 s[8:9], exec
	s_mov_b64 exec, s[44:45]
	v_mov_b32_e32 v1, 1
	s_cmp_lt_u32 s2, 128
	s_cbranch_scc1 .Lgb9_gnoconv
	buffer_wbl2 sc1
	s_waitcnt vmcnt(0)
	v_mov_b32_e32 v0, 0x8a00
	global_atomic_add v0, v1, s[46:47]

; #define SEAM(k) do { if (IN(k) && IN((k) + 1)) flat_barrier((unsigned*)(ws + WS_BAR + 65536), fgen, (unsigned)G); } while (0)
; #define SEAM(k) do { if (IN(k) && IN((k) + 1)) xcd_barrier(xbar); } while (0)
; __device__ __forceinline__ void panel_sync(unsigned* cnt, int pm, int wid, int lane) {
;     ...
;         unsigned sp = 0;
;         while ((unsigned)__builtin_amdgcn_readfirstlane(__hip_atomic_load(cnt + 64 * pm, __ATOMIC_RELAXED, __HIP_MEMORY_SCOPE_AGENT)) < 4u) { __builtin_amdgcn_s_sleep(2); if (++sp > (1u << 22)) break; }
;         __builtin_amdgcn_fence(__ATOMIC_ACQUIRE, "agent");
;         asm volatile("s_waitcnt vmcnt(0)" ::: "memory");
; __global__ void __launch_bounds__(NT, 2) hymba_fwd(Args args) {
;     ...
;     SEAM(11);
.Lgb9_gpoll:
	global_load_dword v4, v0, s[12:13] sc1
	s_waitcnt vmcnt(0)
	v_readfirstlane_b32 s14, v4
	s_cmp_ge_u32 s14, 20
	s_cbranch_scc1 .Lgb9_gpanel
	s_sleep 1
	s_add_i32 s19, s19, 1
	s_cmp_lt_u32 s19, 20000
	s_cbranch_scc1 .Lgb9_gpoll
.Lgb9_gpanel:
	v_mov_b32_e32 v0, 0x8a00
.Lgb9_gwpoll:
	global_load_dword v4, v0, s[46:47] sc1
	s_waitcnt vmcnt(0)
	v_readfirstlane_b32 s14, v4
	s_cmp_ge_u32 s14, 128
	s_cbranch_scc1 .Lgb9_gacq
	s_sleep 1
	s_add_i32 s19, s19, 1
	s_cmp_lt_u32 s19, 20000
	s_cbranch_scc1 .Lgb9_gwpoll

;     __host__ __device__ bool next(int i, Unit& u) const {
;         const long L = (long)i * G + c; if (L >= nwg) return false;
;         int wgid = (int)L; { const int q = nwg / NXCD, r = nwg % NXCD, xcd = wgid % NXCD, off = wgid / NXCD; wgid = (xcd < r ? xcd * (q + 1) : r * (q + 1) + (xcd - r) * q) + off; }
;         const int nig = WGM * nN, gid = wgid / nig, fm = gid * WGM, gsz = (nM - fm) < WGM ? (nM - fm) : WGM;
;         u.pm = fm + ((wgid % nig) % gsz); u.pn = (wgid % nig) / gsz; return true;
; __global__ void __launch_bounds__(NT, 2) hymba_fwd(Args args) {
;     ...
;     if (IN(12)) {
;         pg8::Gemm g{Hb, (const bf16*)(ws + WS_WD2), M, D, FF}; pg8::StaticOrder S; S.init(M, D, G, bx);
;         pg8::EpiFinal E{XB, args.out, ssq + 4 * M, (unsigned*)(ws + WS_CNT), args.in[I_FINN], 0.5f}; pg8::gemm_phase<pg8::EpiFinal, pg8::StaticOrder, false, true>(lds, g, S, E);
.Lgb9_after:
.LBB0_1410:
	s_cmp_lt_i32 s50, 13
	s_cselect_b64 s[6:7], -1, 0
	s_and_b64 s[4:5], s[6:7], s[4:5]
	s_andn2_b64 vcc, exec, s[4:5]
	s_cbranch_vccnz .LBB0_1468
	s_cmpk_gt_i32 s2, 0xff
	s_waitcnt lgkmcnt(0)
	v_readfirstlane_b32 s24, v209
	s_cbranch_scc1 .LBB0_1468
	s_ashr_i32 s26, s2, 31
	s_lshr_b32 s4, s26, 29
	s_add_i32 s8, s2, s4
	s_and_b32 s4, s8, -8
	s_sub_i32 s6, s2, s4
	s_cmp_gt_i32 s6, -1
	s_cbranch_scc0 .LBB0_1414
	s_lshl_b32 s7, s6, 5
	s_ashr_i32 s5, s8, 3
	s_cbranch_execz .LBB0_1415
	s_branch .LBB0_1416
